# DA fast path prio levels: MFMA clusters 2, A-wave softmax 1, B-wave softmax 0
# speedup vs baseline: 1.0085x; 1.0085x over previous
; template <int NC, int DQK, int DV, bool CAUSAL, bool PF> ...
;     ...
;     _Pragma("unroll") for (int c = 0; c < NC; ++c) {
;       f32x4 s[4];
;       _Pragma("unroll") for (int m = 0; m < 4; ++m) s[m] = f32x4{0.f, 0.f, 0.f, 0.f};
;       _Pragma("unroll") for (int ks = 0; ks < NKS; ++ks) _Pragma("unroll") for (int m = 0; m < 4; ++m) {
;         bf16x8 a = *(const bf16x8*)&Kb[(16 * m + fr) * KLD + c * DQK + ks * 32 + fq * 8];
;         s[m] = __builtin_amdgcn_mfma_f32_16x16x32_bf16(a, qf[c][ks], s[m], 0, 0, 0);
;       }
;       constexpr float THR = 8.f;
;       float tnew, psum = 0.f;
;       if (general) {
;         float tmax = -1e30f;
;         _Pragma("unroll") for (int m = 0; m < 4; ++m) _Pragma("unroll") for (int j = 0; j < 4; ++j) {
;           float v = s[m][j] * scale_log2 + bv[m][j];
;           s[m][j] = v; tmax = fmaxf(tmax, v);
;         }
;         tnew = tmax;
;       } else {
;         float rmax = fmaxf(fmaxf(s[0][0], s[0][1]), fmaxf(s[0][2], s[0][3]));
;         _Pragma("unroll") for (int m = 1; m < 4; ++m) rmax = fmaxf(rmax, fmaxf(fmaxf(s[m][0], s[m][1]), fmaxf(s[m][2], s[m][3])));
;         tnew = rmax * scale_log2 + bb;
;       }
;       if (__builtin_amdgcn_ballot_w64(tnew - mrun[c] > THR) != 0ull) {
.Lda_fast:
	s_setprio 2
	v_add3_u32 v172, s38, v32, v195
	v_add3_u32 v173, s37, v32, v193
	ds_read_b128 v[146:149], v172
	ds_read_b128 v[150:153], v172 offset:4608
	ds_read_b128 v[154:157], v172 offset:9216
	ds_read_b128 v[158:161], v172 offset:13824
	ds_read_b128 v[16:19], v172 offset:64
	ds_read_b128 v[20:23], v172 offset:4672
	ds_read_b128 v[24:27], v172 offset:9280
	ds_read_b128 v[28:31], v172 offset:13888
	ds_read_b128 v[0:3], v172 offset:128
	ds_read_b128 v[4:7], v172 offset:4736
	ds_read_b128 v[8:11], v172 offset:9344
	ds_read_b128 v[12:15], v172 offset:13952
	s_waitcnt lgkmcnt(10)
	v_mfma_f32_16x16x32_bf16 v[146:149], v[146:149], v[138:141], 0
	v_mfma_f32_16x16x32_bf16 v[150:153], v[150:153], v[138:141], 0
	s_waitcnt lgkmcnt(8)
	v_mfma_f32_16x16x32_bf16 v[154:157], v[154:157], v[138:141], 0
	v_mfma_f32_16x16x32_bf16 v[158:161], v[158:161], v[138:141], 0
	s_waitcnt lgkmcnt(4)
	v_mfma_f32_16x16x32_bf16 v[146:149], v[16:19], v[134:137], v[146:149]
	v_mfma_f32_16x16x32_bf16 v[150:153], v[20:23], v[134:137], v[150:153]
	v_mfma_f32_16x16x32_bf16 v[154:157], v[24:27], v[134:137], v[154:157]
	v_mfma_f32_16x16x32_bf16 v[158:161], v[28:31], v[134:137], v[158:161]
	ds_read_b128 v[16:19], v172 offset:192
	ds_read_b128 v[20:23], v172 offset:4800
	ds_read_b128 v[24:27], v172 offset:9408
	ds_read_b128 v[28:31], v172 offset:14016
	ds_read_b128 v[122:125], v173 offset:36864
	ds_read_b128 v[126:129], v173 offset:39424
	ds_read_b128 v[130:133], v173 offset:41984
	ds_read_b128 v[142:145], v173 offset:44544
	s_waitcnt lgkmcnt(8)
	v_mfma_f32_16x16x32_bf16 v[0:3], v[0:3], v[118:121], 0
	v_mfma_f32_16x16x32_bf16 v[4:7], v[4:7], v[118:121], 0
	v_mfma_f32_16x16x32_bf16 v[8:11], v[8:11], v[118:121], 0
	v_mfma_f32_16x16x32_bf16 v[12:15], v[12:15], v[118:121], 0
	s_setprio 1
	v_max3_f32 v174, v146, v147, v148
	v_max3_f32 v175, v149, v150, v151
	v_max3_f32 v174, v174, v152, v153
	v_max3_f32 v175, v175, v154, v155
	v_max3_f32 v174, v174, v156, v157
	v_max3_f32 v175, v175, v158, v159
	v_max3_f32 v174, v174, v160, v161
	v_max_f32_e32 v174, v174, v175
	v_fmamk_f32 v174, v174, 0x3e38aa3b, v170
	v_sub_f32_e32 v175, v174, v194
	v_cmp_lt_f32_e32 vcc, s33, v175
	s_cbranch_vccnz .Lda_resc0

; __device__ __forceinline__ uint2 pack4(float a, float b, float c, float d) { uint2 r; r.x = pk2(a, b); r.y = pk2(c, d); return r; }
; template <int NC, int DQK, int DV, bool CAUSAL, bool PF> ...
;     ...
;         float cc = bb - mrun[c];
;         _Pragma("unroll") for (int m = 0; m < 4; ++m) _Pragma("unroll") for (int j = 0; j < 4; ++j) { float pv = __builtin_amdgcn_exp2f(s[m][j] * scale_log2 + cc); s[m][j] = pv; psum += pv; }
;       }
;       lsum[c] += psum;
;       _Pragma("unroll") for (int k2 = 0; k2 < 2; ++k2) {
;         uint2 lo = pack4(s[2 * k2][0], s[2 * k2][1], s[2 * k2][2], s[2 * k2][3]);
;         uint2 hi = pack4(s[2 * k2 + 1][0], s[2 * k2 + 1][1], s[2 * k2 + 1][2], s[2 * k2 + 1][3]);
;         uint4 pk; pk.x = lo.x; pk.y = lo.y; pk.z = hi.x; pk.w = hi.y;
;         pf[c][k2] = *(bf16x8*)&pk;
;       }
;     }
;     _Pragma("unroll") for (int k2 = 0; k2 < 2; ++k2) _Pragma("unroll") for (int v = 0; v < NVT; ++v) {
;       bf16x8 a = *(const bf16x8*)&Vb[(16 * v + fr) * VLD + 32 * k2 + fq * 8];
;       _Pragma("unroll") for (int c = 0; c < NC; ++c) O[c][v] = __builtin_amdgcn_mfma_f32_16x16x32_bf16(a, pf[c][k2], O[c][v], 0, 0, 0);
;       if ((v & 3) == 3) __builtin_amdgcn_sched_barrier(0);
;     }
.Lda_resc1_ret:
	v_sub_f32_e32 v175, v170, v171
	v_fmamk_f32 v0, v0, 0x3e38aa3b, v175
	v_fmamk_f32 v1, v1, 0x3e38aa3b, v175
	v_fmamk_f32 v2, v2, 0x3e38aa3b, v175
	v_fmamk_f32 v3, v3, 0x3e38aa3b, v175
	v_fmamk_f32 v4, v4, 0x3e38aa3b, v175
	v_fmamk_f32 v5, v5, 0x3e38aa3b, v175
	v_fmamk_f32 v6, v6, 0x3e38aa3b, v175
	v_fmamk_f32 v7, v7, 0x3e38aa3b, v175
	v_fmamk_f32 v8, v8, 0x3e38aa3b, v175
	v_fmamk_f32 v9, v9, 0x3e38aa3b, v175
	v_fmamk_f32 v10, v10, 0x3e38aa3b, v175
	v_fmamk_f32 v11, v11, 0x3e38aa3b, v175
	v_fmamk_f32 v12, v12, 0x3e38aa3b, v175
	v_fmamk_f32 v13, v13, 0x3e38aa3b, v175
	v_fmamk_f32 v14, v14, 0x3e38aa3b, v175
	v_fmamk_f32 v15, v15, 0x3e38aa3b, v175
	v_exp_f32_e32 v0, v0
	v_exp_f32_e32 v1, v1
	v_exp_f32_e32 v2, v2
	v_add_f32_e32 v174, v1, v0
	v_exp_f32_e32 v3, v3
	v_add_f32_e32 v174, v2, v174
	v_exp_f32_e32 v4, v4
	v_add_f32_e32 v174, v3, v174
	v_exp_f32_e32 v5, v5
	v_add_f32_e32 v174, v4, v174
	v_exp_f32_e32 v6, v6
	v_add_f32_e32 v174, v5, v174
	v_exp_f32_e32 v7, v7
	v_add_f32_e32 v174, v6, v174
	v_exp_f32_e32 v8, v8
	v_add_f32_e32 v174, v7, v174
	v_exp_f32_e32 v9, v9
	v_add_f32_e32 v174, v8, v174
	v_exp_f32_e32 v10, v10
	v_add_f32_e32 v174, v9, v174
	v_exp_f32_e32 v11, v11
	v_add_f32_e32 v174, v10, v174
	v_exp_f32_e32 v12, v12
	v_add_f32_e32 v174, v11, v174
	v_exp_f32_e32 v13, v13
	v_add_f32_e32 v174, v12, v174
	v_exp_f32_e32 v14, v14
	v_add_f32_e32 v174, v13, v174
	v_exp_f32_e32 v15, v15
	v_add_f32_e32 v174, v14, v174
	v_cvt_pk_bf16_f32 v0, v0, v1
	v_add_f32_e32 v174, v15, v174
	v_cvt_pk_bf16_f32 v1, v2, v3
	v_add_f32_e32 v191, v191, v174
	v_cvt_pk_bf16_f32 v2, v4, v5
	v_cvt_pk_bf16_f32 v3, v6, v7
	v_cvt_pk_bf16_f32 v4, v8, v9
	v_cvt_pk_bf16_f32 v5, v10, v11
	v_cvt_pk_bf16_f32 v6, v12, v13
	v_cvt_pk_bf16_f32 v7, v14, v15
	ds_read_b128 v[8:11], v173 offset:42048
	ds_read_b128 v[12:15], v173 offset:44608
	s_setprio 2
	s_waitcnt lgkmcnt(10)
	v_mfma_f32_16x16x32_bf16 v[106:109], v[122:125], v[146:149], v[106:109]
	v_mfma_f32_16x16x32_bf16 v[110:113], v[122:125], v[0:3], v[110:113]
	v_mfma_f32_16x16x32_bf16 v[98:101], v[126:129], v[146:149], v[98:101]
	v_mfma_f32_16x16x32_bf16 v[102:105], v[126:129], v[0:3], v[102:105]
	s_waitcnt lgkmcnt(8)
	v_mfma_f32_16x16x32_bf16 v[90:93], v[130:133], v[146:149], v[90:93]
	v_mfma_f32_16x16x32_bf16 v[94:97], v[130:133], v[0:3], v[94:97]
	v_mfma_f32_16x16x32_bf16 v[78:81], v[142:145], v[146:149], v[78:81]
	v_mfma_f32_16x16x32_bf16 v[74:77], v[142:145], v[0:3], v[74:77]
	ds_read_b128 v[122:125], v173 offset:47168
	ds_read_b128 v[126:129], v173 offset:49728
	ds_read_b128 v[130:133], v173 offset:52288
	ds_read_b128 v[142:145], v173 offset:54848
	s_waitcnt lgkmcnt(10)
	v_mfma_f32_16x16x32_bf16 v[62:65], v[16:19], v[146:149], v[62:65]
	v_mfma_f32_16x16x32_bf16 v[70:73], v[16:19], v[0:3], v[70:73]
	v_mfma_f32_16x16x32_bf16 v[50:53], v[20:23], v[146:149], v[50:53]
	v_mfma_f32_16x16x32_bf16 v[66:69], v[20:23], v[0:3], v[66:69]
	s_waitcnt lgkmcnt(8)
	v_mfma_f32_16x16x32_bf16 v[54:57], v[24:27], v[146:149], v[54:57]
	v_mfma_f32_16x16x32_bf16 v[58:61], v[24:27], v[0:3], v[58:61]
	v_mfma_f32_16x16x32_bf16 v[82:85], v[28:31], v[146:149], v[82:85]
	v_mfma_f32_16x16x32_bf16 v[86:89], v[28:31], v[0:3], v[86:89]
	s_waitcnt lgkmcnt(6)
	v_mfma_f32_16x16x32_bf16 v[106:109], v[154:157], v[150:153], v[106:109]
	v_mfma_f32_16x16x32_bf16 v[110:113], v[154:157], v[4:7], v[110:113]
	v_mfma_f32_16x16x32_bf16 v[98:101], v[158:161], v[150:153], v[98:101]
	v_mfma_f32_16x16x32_bf16 v[102:105], v[158:161], v[4:7], v[102:105]
	s_waitcnt lgkmcnt(4)
	v_mfma_f32_16x16x32_bf16 v[90:93], v[8:11], v[150:153], v[90:93]
	v_mfma_f32_16x16x32_bf16 v[94:97], v[8:11], v[4:7], v[94:97]
	v_mfma_f32_16x16x32_bf16 v[78:81], v[12:15], v[150:153], v[78:81]
	v_mfma_f32_16x16x32_bf16 v[74:77], v[12:15], v[4:7], v[74:77]
	s_waitcnt lgkmcnt(2)
	v_mfma_f32_16x16x32_bf16 v[62:65], v[122:125], v[150:153], v[62:65]
	v_mfma_f32_16x16x32_bf16 v[70:73], v[122:125], v[4:7], v[70:73]
	v_mfma_f32_16x16x32_bf16 v[50:53], v[126:129], v[150:153], v[50:53]
	v_mfma_f32_16x16x32_bf16 v[66:69], v[126:129], v[4:7], v[66:69]
	s_waitcnt lgkmcnt(0)
	v_mfma_f32_16x16x32_bf16 v[54:57], v[130:133], v[150:153], v[54:57]
	v_mfma_f32_16x16x32_bf16 v[58:61], v[130:133], v[4:7], v[58:61]
	v_mfma_f32_16x16x32_bf16 v[82:85], v[142:145], v[150:153], v[82:85]
	v_mfma_f32_16x16x32_bf16 v[86:89], v[142:145], v[4:7], v[86:89]
	s_setprio 0
	s_branch .LBB0_1784

; template <int NC, int DQK, int DV, bool CAUSAL, bool PF> ...
;     ...
;       _Pragma("unroll") for (int ks = 0; ks < NKS; ++ks) _Pragma("unroll") for (int m = 0; m < 4; ++m) {
;         bf16x8 a = *(const bf16x8*)&Kb[(16 * m + fr) * KLD + c * DQK + ks * 32 + fq * 8];
;         s[m] = __builtin_amdgcn_mfma_f32_16x16x32_bf16(a, qf[c][ks], s[m], 0, 0, 0);
;     ...
;     _Pragma("unroll") for (int k2 = 0; k2 < 2; ++k2) _Pragma("unroll") for (int v = 0; v < NVT; ++v) {
;       bf16x8 a = *(const bf16x8*)&Vb[(16 * v + fr) * VLD + 32 * k2 + fq * 8];
;       _Pragma("unroll") for (int c = 0; c < NC; ++c) O[c][v] = __builtin_amdgcn_mfma_f32_16x16x32_bf16(a, pf[c][k2], O[c][v], 0, 0, 0);
;       if ((v & 3) == 3) __builtin_amdgcn_sched_barrier(0);
;     }
.Ldb_fastB:
	s_setprio 2
	v_add3_u32 v172, s38, v32, v195
	s_cmp_eq_u32 s34, 0
	s_cbranch_scc1 .Ldb_B_nopend
	s_sub_i32 s8, s37, 0x5000
	s_cmp_lt_i32 s8, 0
	s_cselect_b32 s8, 0xa000, s8
	v_add3_u32 v173, s8, v32, v193
	ds_read_b128 v[0:3], v173 offset:36864
	ds_read_b128 v[4:7], v173 offset:39424
	ds_read_b128 v[8:11], v173 offset:41984
	ds_read_b128 v[12:15], v173 offset:44544
	ds_read_b128 v[16:19], v173 offset:47104
	ds_read_b128 v[20:23], v173 offset:49664
	ds_read_b128 v[24:27], v173 offset:52224
	ds_read_b128 v[28:31], v173 offset:54784
	ds_read_b128 v[122:125], v173 offset:36928
	ds_read_b128 v[126:129], v173 offset:39488
	ds_read_b128 v[130:133], v173 offset:42048
	ds_read_b128 v[142:145], v173 offset:44608
	s_waitcnt lgkmcnt(10)
	v_mfma_f32_16x16x32_bf16 v[106:109], v[0:3], v[146:149], v[106:109]
	v_mfma_f32_16x16x32_bf16 v[110:113], v[0:3], v[154:157], v[110:113]
	v_mfma_f32_16x16x32_bf16 v[98:101], v[4:7], v[146:149], v[98:101]
	v_mfma_f32_16x16x32_bf16 v[102:105], v[4:7], v[154:157], v[102:105]
	s_waitcnt lgkmcnt(8)
	v_mfma_f32_16x16x32_bf16 v[90:93], v[8:11], v[146:149], v[90:93]
	v_mfma_f32_16x16x32_bf16 v[94:97], v[8:11], v[154:157], v[94:97]
	v_mfma_f32_16x16x32_bf16 v[78:81], v[12:15], v[146:149], v[78:81]
	v_mfma_f32_16x16x32_bf16 v[74:77], v[12:15], v[154:157], v[74:77]
	ds_read_b128 v[0:3], v173 offset:47168
	ds_read_b128 v[4:7], v173 offset:49728
	ds_read_b128 v[8:11], v173 offset:52288
	ds_read_b128 v[12:15], v173 offset:54848
	s_waitcnt lgkmcnt(10)
	v_mfma_f32_16x16x32_bf16 v[62:65], v[16:19], v[146:149], v[62:65]
	v_mfma_f32_16x16x32_bf16 v[70:73], v[16:19], v[154:157], v[70:73]
	v_mfma_f32_16x16x32_bf16 v[50:53], v[20:23], v[146:149], v[50:53]
	v_mfma_f32_16x16x32_bf16 v[66:69], v[20:23], v[154:157], v[66:69]
	s_waitcnt lgkmcnt(8)
	v_mfma_f32_16x16x32_bf16 v[54:57], v[24:27], v[146:149], v[54:57]
	v_mfma_f32_16x16x32_bf16 v[58:61], v[24:27], v[154:157], v[58:61]
	v_mfma_f32_16x16x32_bf16 v[82:85], v[28:31], v[146:149], v[82:85]
	v_mfma_f32_16x16x32_bf16 v[86:89], v[28:31], v[154:157], v[86:89]
	ds_read_b128 v[16:19], v172 offset:64
	ds_read_b128 v[20:23], v172 offset:4672
	ds_read_b128 v[24:27], v172 offset:9280
	ds_read_b128 v[28:31], v172 offset:13888
	s_waitcnt lgkmcnt(10)
	v_mfma_f32_16x16x32_bf16 v[106:109], v[122:125], v[150:153], v[106:109]
	v_mfma_f32_16x16x32_bf16 v[110:113], v[122:125], v[158:161], v[110:113]
	v_mfma_f32_16x16x32_bf16 v[98:101], v[126:129], v[150:153], v[98:101]
	v_mfma_f32_16x16x32_bf16 v[102:105], v[126:129], v[158:161], v[102:105]
	s_waitcnt lgkmcnt(8)
	v_mfma_f32_16x16x32_bf16 v[90:93], v[130:133], v[150:153], v[90:93]
	v_mfma_f32_16x16x32_bf16 v[94:97], v[130:133], v[158:161], v[94:97]
	v_mfma_f32_16x16x32_bf16 v[78:81], v[142:145], v[150:153], v[78:81]
	v_mfma_f32_16x16x32_bf16 v[74:77], v[142:145], v[158:161], v[74:77]
	ds_read_b128 v[122:125], v172
	ds_read_b128 v[126:129], v172 offset:4608
	ds_read_b128 v[130:133], v172 offset:9216
	ds_read_b128 v[142:145], v172 offset:13824
	s_waitcnt lgkmcnt(10)
	v_mfma_f32_16x16x32_bf16 v[62:65], v[0:3], v[150:153], v[62:65]
	v_mfma_f32_16x16x32_bf16 v[70:73], v[0:3], v[158:161], v[70:73]
	v_mfma_f32_16x16x32_bf16 v[50:53], v[4:7], v[150:153], v[50:53]
	v_mfma_f32_16x16x32_bf16 v[66:69], v[4:7], v[158:161], v[66:69]
	s_waitcnt lgkmcnt(8)
	v_mfma_f32_16x16x32_bf16 v[54:57], v[8:11], v[150:153], v[54:57]
	v_mfma_f32_16x16x32_bf16 v[58:61], v[8:11], v[158:161], v[58:61]
	v_mfma_f32_16x16x32_bf16 v[82:85], v[12:15], v[150:153], v[82:85]
	v_mfma_f32_16x16x32_bf16 v[86:89], v[12:15], v[158:161], v[86:89]
	ds_read_b128 v[0:3], v172 offset:128
	ds_read_b128 v[4:7], v172 offset:4736
	ds_read_b128 v[8:11], v172 offset:9344
	ds_read_b128 v[12:15], v172 offset:13952
	s_branch .Ldb_B_qk
